# c24 with the DIFF deferred-rescale threshold raised from 64 to 80 log2 units (P <= 2^80 still far inside f32/bf16 range; fewer rescale events)
# speedup vs baseline: 1.0133x; 1.0020x over previous
.LBB0_1398:
	s_cmp_lt_i32 s62, 11
	s_cselect_b64 s[0:1], -1, 0
	s_and_b64 s[2:3], s[0:1], s[4:5]
	s_andn2_b64 vcc, exec, s[2:3]
	s_cbranch_vccnz .LBB0_1484
	v_mbcnt_hi_u32_b32 v2, -1, v228
	v_mov_b32_e32 v0, v2
	s_mov_b64 s[14:15], s[24:25]
	s_load_dwordx8 s[4:11], s[14:15], 0x40
	v_ashrrev_i32_e32 v1, 31, v0
	v_lshlrev_b64 v[4:5], 2, v[0:1]
	v_xor_b32_e32 v8, 2, v2
	v_xor_b32_e32 v9, 4, v2
	s_waitcnt lgkmcnt(0)
	v_lshl_add_u64 v[6:7], s[4:5], 0, v[4:5]
	global_load_dword v1, v[6:7], off
	v_lshl_add_u64 v[6:7], s[6:7], 0, v[4:5]
	global_load_dword v3, v[6:7], off
	v_lshl_add_u64 v[6:7], s[8:9], 0, v[4:5]
	v_lshl_add_u64 v[4:5], s[10:11], 0, v[4:5]
	global_load_dword v6, v[6:7], off
	v_xor_b32_e32 v7, 1, v2
	global_load_dword v4, v[4:5], off
	v_and_b32_e32 v5, 64, v2
	v_add_u32_e32 v5, 64, v5
	v_cmp_lt_i32_e32 vcc, v7, v5
	v_xor_b32_e32 v10, 8, v2
	v_xor_b32_e32 v11, 16, v2
	v_cndmask_b32_e32 v7, v2, v7, vcc
	v_lshlrev_b32_e32 v198, 2, v7
	v_cmp_lt_i32_e32 vcc, v8, v5
	v_xor_b32_e32 v12, 32, v2
	v_readlane_b32 s0, v244, 2
	v_cndmask_b32_e32 v8, v2, v8, vcc
	v_lshlrev_b32_e32 v199, 2, v8
	v_cmp_lt_i32_e32 vcc, v9, v5
	s_cmpk_gt_i32 s0, 0xff
	s_waitcnt vmcnt(0)
	v_mul_f32_e32 v7, v1, v3
	ds_bpermute_b32 v7, v198, v7
	v_mul_f32_e32 v13, v6, v4
	ds_bpermute_b32 v13, v198, v13
	s_waitcnt lgkmcnt(1)
	v_fmac_f32_e32 v7, v1, v3
	ds_bpermute_b32 v1, v199, v7
	s_waitcnt lgkmcnt(1)
	v_fmac_f32_e32 v13, v6, v4
	ds_bpermute_b32 v3, v199, v13
	v_cndmask_b32_e32 v4, v2, v9, vcc
	v_lshlrev_b32_e32 v200, 2, v4
	s_waitcnt lgkmcnt(1)
	v_add_f32_e32 v1, v7, v1
	ds_bpermute_b32 v4, v200, v1
	s_waitcnt lgkmcnt(1)
	v_add_f32_e32 v3, v13, v3
	ds_bpermute_b32 v6, v200, v3
	v_cmp_lt_i32_e32 vcc, v10, v5
	s_waitcnt lgkmcnt(1)
	v_add_f32_e32 v1, v1, v4
	v_cndmask_b32_e32 v7, v2, v10, vcc
	v_lshlrev_b32_e32 v201, 2, v7
	s_waitcnt lgkmcnt(0)
	v_add_f32_e32 v3, v3, v6
	ds_bpermute_b32 v4, v201, v1
	ds_bpermute_b32 v6, v201, v3
	v_cmp_lt_i32_e32 vcc, v11, v5
	s_waitcnt lgkmcnt(1)
	v_add_f32_e32 v1, v1, v4
	v_cndmask_b32_e32 v7, v2, v11, vcc
	v_lshlrev_b32_e32 v202, 2, v7
	s_waitcnt lgkmcnt(0)
	v_add_f32_e32 v3, v3, v6
	ds_bpermute_b32 v4, v202, v1
	ds_bpermute_b32 v6, v202, v3
	v_cmp_lt_i32_e32 vcc, v12, v5
	s_waitcnt lgkmcnt(1)
	v_add_f32_e32 v4, v1, v4
	v_cndmask_b32_e32 v5, v2, v12, vcc
	v_lshlrev_b32_e32 v7, 2, v5
	s_waitcnt lgkmcnt(0)
	v_add_f32_e32 v1, v3, v6
	ds_bpermute_b32 v5, v7, v4
	ds_bpermute_b32 v3, v7, v1
	s_cbranch_scc1 .LBB0_1484
	v_writelane_b32 v244, s2, 11
	s_load_dwordx2 s[0:1], s[14:15], 0xa8
	s_load_dwordx2 s[6:7], s[14:15], 0x60
	v_writelane_b32 v244, s3, 12
	v_writelane_b32 v244, s88, 13
	s_and_b32 s2, s91, 0xffffffc0
	s_waitcnt lgkmcnt(0)
	s_add_u32 s3, s0, 0x7200000
	v_writelane_b32 v244, s89, 14
	v_writelane_b32 v244, s91, 15
	v_writelane_b32 v244, s3, 16
	s_addc_u32 s3, s1, 0
	v_writelane_b32 v244, s3, 17
	s_add_u32 s3, s0, 0x9200000
	v_writelane_b32 v244, s3, 18
	s_addc_u32 s3, s1, 0
	v_add_u32_e32 v203, s2, v0
	v_writelane_b32 v244, s3, 19
	v_add_u32_e32 v205, s2, v2
	s_mov_b32 s2, s92
	s_ashr_i32 s93, s92, 31
	v_writelane_b32 v244, s2, 20
	v_add_f32_e32 v4, v4, v5
	v_add_f32_e32 v0, v1, v3
	v_writelane_b32 v244, s3, 21
	s_lshl_b64 s[2:3], s[92:93], 17
	s_add_u32 s2, s0, s2
	v_mul_f32_e32 v1, 0x3fb8aa3b, v4
	v_mul_f32_e32 v0, 0x3fb8aa3b, v0
	s_addc_u32 s3, s1, s3
	v_exp_f32_e32 v1, v1
	v_exp_f32_e32 v0, v0
	s_add_u32 s8, s2, 0x3200000
	s_addc_u32 s9, s3, 0
	v_writelane_b32 v244, s90, 22
	s_lshl_b32 s2, s90, 5
	v_writelane_b32 v244, s2, 23
	s_add_u32 s0, s0, 0x92c1000
	v_writelane_b32 v244, s0, 24
	s_addc_u32 s0, s1, 0
	v_sub_f32_e32 v0, v1, v0
	v_writelane_b32 v244, s0, 25
	v_add_f32_e32 v204, 0x3eb60549, v0
	v_mov_b32_e32 v3, 0
	s_mov_b64 s[10:11], 0x800
	s_mov_b64 s[14:15], 0x30000
	s_mov_b64 s[16:17], 0xc0000
	s_mov_b32 s68, 0x42a00000
	s_mov_b32 s72, 0x19000
	s_mov_b32 s73, 0x11000
	s_mov_b32 s74, 0x9000
	s_mov_b32 s75, 0xa000
	s_mov_b32 s76, 0x12000
	s_mov_b32 s77, 0x1a000
	s_mov_b32 s78, 0x1b000
	s_mov_b32 s79, 0x13000
	s_mov_b32 s84, 0xb000
	s_movk_i32 s85, 0x3000
	s_mov_b32 s86, 0x14000
	s_mov_b32 s87, 0x1c000
	s_mov_b32 s88, 0x1d000
	s_mov_b32 s89, 0x15000
	s_mov_b32 s90, 0xd000
	s_movk_i32 s91, 0x5000
	s_mov_b32 s92, 0xe000
	s_mov_b32 s93, 0x16000
	s_mov_b32 s94, 0x1e000
	s_mov_b32 s95, 0x17000
	s_mov_b32 s96, 0xf000
	s_movk_i32 s97, 0x7000
	v_mov_b32_e32 v206, 0x358637bd
	s_movk_i32 s30, 0x7fff
	v_mov_b32_e32 v207, 0x3f80
	v_mov_b32_e32 v208, 0x3f803f80
	v_mov_b32_e32 v209, 0x1800
	v_readlane_b32 s3, v244, 2
	s_branch .LBB0_1402
